# grid barrier: every workgroup spins on the top-level arrival counter (TOP >= (gen+1)*nx) instead of TOPGEN / per-XCD XGEN; the XGEN publish and its waits removed
# speedup vs baseline: 1.0089x; 1.0089x over previous
.LBB0_710:
	v_readlane_b32 s12, v255, 4
	v_readlane_b32 s13, v255, 5
	v_cvt_f32_u32_e32 v0, v3
	v_sub_u32_e32 v5, 0, v3
	v_rcp_iflag_f32_e32 v0, v0
	s_nop 1
	global_atomic_add v4, v1, v233, s[12:13] sc0
	v_mul_f32_e32 v0, 0x4f7ffffe, v0
	v_cvt_u32_f32_e32 v0, v0
	v_mul_lo_u32 v5, v5, v0
	v_mul_hi_u32 v5, v0, v5
	v_add_u32_e32 v0, v0, v5
	s_waitcnt vmcnt(0)
	v_mul_hi_u32 v0, v4, v0
	v_mul_lo_u32 v5, v0, v3
	v_sub_u32_e32 v5, v4, v5
	v_add_u32_e32 v6, 1, v0
	v_cmp_ge_u32_e32 vcc, v5, v3
	v_add_u32_e32 v4, 1, v4
	s_nop 0
	v_cndmask_b32_e32 v0, v0, v6, vcc
	v_sub_u32_e32 v6, v5, v3
	v_cndmask_b32_e32 v5, v5, v6, vcc
	v_add_u32_e32 v6, 1, v0
	v_cmp_ge_u32_e32 vcc, v5, v3
	s_nop 1
	v_cndmask_b32_e32 v0, v0, v6, vcc
	v_mul_lo_u32 v5, v3, v0
	v_add_u32_e32 v3, v5, v3
	v_cmp_ne_u32_e32 vcc, v4, v3
	s_and_saveexec_b64 s[12:13], vcc
	s_xor_b64 s[28:29], exec, s[12:13]
	s_cbranch_execz .LBB0_724
	v_readlane_b32 s12, v255, 8
	v_readlane_b32 s13, v255, 9
	s_waitcnt lgkmcnt(0)
	v_mad_u32_u24 v40, v0, v2, v2
	s_nop 3
	global_load_dword v2, v1, s[12:13] sc1
	s_waitcnt vmcnt(0)
	v_sub_u32_e32 v2, v2, v40
	v_cmp_gt_i32_e32 vcc, 0, v2
	s_and_saveexec_b64 s[30:31], vcc
	s_cbranch_execz .LBB0_723
	s_mov_b32 s2, 1
	s_mov_b64 s[36:37], 0
	s_branch .LBB0_714

.LBB0_718:
	v_readlane_b32 s12, v255, 8
	v_readlane_b32 s13, v255, 9
	s_add_i32 s2, s2, 1
	s_mov_b64 s[42:43], -1
	s_nop 2
	global_load_dword v2, v1, s[12:13] sc1
	s_waitcnt vmcnt(0)
	v_sub_u32_e32 v2, v2, v40
	v_cmp_le_i32_e32 vcc, 0, v2
	s_orn2_b64 s[40:41], vcc, exec
	s_branch .LBB0_713

.LBB0_727:
	s_or_b64 exec, exec, s[30:31]
	s_waitcnt vmcnt(0)
	v_readfirstlane_b32 s2, v3
	v_sub_u32_e32 v4, 0, v2
	v_readlane_b32 s12, v255, 10
	v_add_u32_e32 v3, s2, v0
	v_cvt_f32_u32_e32 v0, v2
	v_readlane_b32 s13, v255, 11
	s_mov_b64 s[30:31], -1
	v_rcp_iflag_f32_e32 v0, v0
	s_nop 0
	v_mul_f32_e32 v0, 0x4f7ffffe, v0
	v_cvt_u32_f32_e32 v0, v0
	v_mul_lo_u32 v4, v4, v0
	v_mul_hi_u32 v4, v0, v4
	v_add_u32_e32 v0, v0, v4
	v_mul_hi_u32 v0, v3, v0
	v_mul_lo_u32 v4, v0, v2
	v_sub_u32_e32 v4, v3, v4
	v_cmp_ge_u32_e32 vcc, v4, v2
	v_add_u32_e32 v5, 1, v0
	v_add_u32_e32 v3, 1, v3
	v_cndmask_b32_e32 v0, v0, v5, vcc
	v_sub_u32_e32 v5, v4, v2
	v_cndmask_b32_e32 v4, v4, v5, vcc
	v_cmp_ge_u32_e32 vcc, v4, v2
	v_add_u32_e32 v4, 1, v0
	s_nop 0
	v_cndmask_b32_e32 v0, v0, v4, vcc
	v_mul_lo_u32 v4, v2, v0
	v_add_u32_e32 v2, v4, v2
	v_cmp_ne_u32_e32 vcc, v3, v2
	v_mov_b32_e32 v40, v2
	v_mov_b64_e32 v[2:3], s[12:13]
	s_and_saveexec_b64 s[28:29], vcc
	s_cbranch_execz .LBB0_739
	v_readlane_b32 s12, v255, 8
	v_readlane_b32 s13, v255, 9
	s_mov_b64 s[36:37], 0
	s_nop 3
	global_load_dword v2, v1, s[12:13] sc1
	s_waitcnt vmcnt(0)
	v_sub_u32_e32 v2, v2, v40
	v_cmp_gt_i32_e32 vcc, 0, v2
	s_and_saveexec_b64 s[30:31], vcc
	s_cbranch_execz .LBB0_738
	s_mov_b32 s2, 1
	s_branch .LBB0_731

.LBB0_741:
	s_or_b64 exec, exec, s[28:29]
.LBB0_742:
	s_or_b64 exec, exec, s[26:27]
	s_waitcnt lgkmcnt(0)
	s_barrier
	s_mov_b64 s[26:27], -1
	s_and_b64 vcc, exec, s[24:25]
	s_cbranch_vccz .LBB0_704
